# P0 weight transposes: gain wait + scale multiplies deferred to the item's last sub-step behind 7 of its weight loads (vmcnt(7)); on top of v134
# baseline (speedup 1.0000x reference)
.Lgh0_skip:
	s_cbranch_scc1 .LBB0_37
.LBB0_37:
	v_mad_u64_u32 v[64:65], s[0:1], v92, s50, 0
	v_mov_b32_e32 v66, v65
	v_mad_u64_u32 v[66:67], s[0:1], v93, s50, v[66:67]
	s_lshl_b32 s44, s43, 5
	v_mov_b32_e32 v65, v66
	s_ashr_i32 s45, s44, 31
	v_lshl_add_u64 v[64:65], v[64:65], 2, s[46:47]
	v_lshl_add_u64 v[64:65], s[44:45], 2, v[64:65]
	v_lshl_add_u64 v[64:65], v[64:65], 0, v[96:97]
	global_load_dwordx4 v[64:67], v[64:65], off nt
	v_cndmask_b32_e64 v68, 0, 1, s[48:49]
	v_cmp_ne_u32_e64 s[0:1], 1, v68
	s_andn2_b64 vcc, exec, s[48:49]
	v_mov_b32_e32 v104, v102
	s_cbranch_vccnz .LBB0_39
.LBB0_39:
	v_or_b32_e32 v68, 8, v92
	v_mad_u64_u32 v[68:69], s[48:49], v68, s50, 0
	v_mov_b32_e32 v70, v69
	v_mad_u64_u32 v[70:71], s[48:49], v93, s50, v[70:71]
	v_mov_b32_e32 v69, v70
	v_lshl_add_u64 v[68:69], v[68:69], 2, s[46:47]
	v_lshl_add_u64 v[68:69], s[44:45], 2, v[68:69]
	v_lshl_add_u64 v[68:69], v[68:69], 0, v[96:97]
	global_load_dwordx4 v[68:71], v[68:69], off nt
	s_and_b64 vcc, exec, s[0:1]
	v_mov_b32_e32 v106, v102
	s_cbranch_vccnz .LBB0_41
.LBB0_41:
	v_or_b32_e32 v72, 16, v92
	v_mad_u64_u32 v[72:73], s[48:49], v72, s50, 0
	v_mov_b32_e32 v74, v73
	v_mad_u64_u32 v[74:75], s[48:49], v93, s50, v[74:75]
	v_mov_b32_e32 v73, v74
	v_lshl_add_u64 v[72:73], v[72:73], 2, s[46:47]
	v_lshl_add_u64 v[72:73], s[44:45], 2, v[72:73]
	v_lshl_add_u64 v[72:73], v[72:73], 0, v[96:97]
	global_load_dwordx4 v[72:75], v[72:73], off nt
	s_and_b64 vcc, exec, s[0:1]
	v_mov_b32_e32 v108, v102
	s_cbranch_vccnz .LBB0_43
.LBB0_43:
	v_or_b32_e32 v76, 24, v92
	v_mad_u64_u32 v[76:77], s[48:49], v76, s50, 0
	v_mov_b32_e32 v78, v77
	v_mad_u64_u32 v[78:79], s[48:49], v93, s50, v[78:79]
	v_mov_b32_e32 v77, v78
	v_lshl_add_u64 v[76:77], v[76:77], 2, s[46:47]
	v_lshl_add_u64 v[76:77], s[44:45], 2, v[76:77]
	v_lshl_add_u64 v[76:77], v[76:77], 0, v[96:97]
	global_load_dwordx4 v[76:79], v[76:77], off nt
	s_and_b64 vcc, exec, s[0:1]
	v_mov_b32_e32 v110, v102
	s_cbranch_vccnz .LBB0_45
.LBB0_45:
	v_or_b32_e32 v80, 32, v92
	v_mad_u64_u32 v[80:81], s[48:49], v80, s50, 0
	v_mov_b32_e32 v82, v81
	v_mad_u64_u32 v[82:83], s[48:49], v93, s50, v[82:83]
	v_mov_b32_e32 v81, v82
	v_lshl_add_u64 v[80:81], v[80:81], 2, s[46:47]
	v_lshl_add_u64 v[80:81], s[44:45], 2, v[80:81]
	v_lshl_add_u64 v[80:81], v[80:81], 0, v[96:97]
	global_load_dwordx4 v[80:83], v[80:81], off nt
	s_and_b64 vcc, exec, s[0:1]
	v_mov_b32_e32 v112, v102
	s_cbranch_vccnz .LBB0_47
.LBB0_47:
	v_or_b32_e32 v84, 40, v92
	v_mad_u64_u32 v[84:85], s[48:49], v84, s50, 0
	v_mov_b32_e32 v86, v85
	v_mad_u64_u32 v[86:87], s[48:49], v93, s50, v[86:87]
	v_mov_b32_e32 v85, v86
	v_lshl_add_u64 v[84:85], v[84:85], 2, s[46:47]
	v_lshl_add_u64 v[84:85], s[44:45], 2, v[84:85]
	v_lshl_add_u64 v[84:85], v[84:85], 0, v[96:97]
	global_load_dwordx4 v[84:87], v[84:85], off nt
	s_and_b64 vcc, exec, s[0:1]
	v_mov_b32_e32 v114, v102
	s_cbranch_vccnz .LBB0_49
.LBB0_49:
	v_or_b32_e32 v88, 48, v92
	v_mad_u64_u32 v[88:89], s[48:49], v88, s50, 0
	v_mov_b32_e32 v90, v89
	v_mad_u64_u32 v[90:91], s[48:49], v93, s50, v[90:91]
	v_mov_b32_e32 v89, v90
	v_lshl_add_u64 v[88:89], v[88:89], 2, s[46:47]
	v_lshl_add_u64 v[88:89], s[44:45], 2, v[88:89]
	v_lshl_add_u64 v[88:89], v[88:89], 0, v[96:97]
	global_load_dwordx4 v[88:91], v[88:89], off nt
	s_and_b64 vcc, exec, s[0:1]
	s_cbranch_vccnz .LBB0_51
	s_waitcnt vmcnt(7)
	v_mul_f32_e32 v100, v102, v140
	v_mul_f32_e32 v104, v102, v141
	v_mul_f32_e32 v106, v102, v142
	v_mul_f32_e32 v108, v102, v143
	v_mul_f32_e32 v110, v102, v144
	v_mul_f32_e32 v112, v102, v145
	v_mul_f32_e32 v114, v102, v146
	v_mul_f32_e32 v102, v102, v147

.Lgh1_skip:
	s_cbranch_scc1 .LBB0_68
.LBB0_68:
	v_mad_u64_u32 v[0:1], s[0:1], v46, s57, 0
	v_mov_b32_e32 v2, v1
	v_mad_u64_u32 v[2:3], s[0:1], v47, s57, v[2:3]
	s_lshl_b32 s50, s54, 5
	v_mov_b32_e32 v1, v2
	s_ashr_i32 s51, s50, 31
	v_lshl_add_u64 v[0:1], v[0:1], 2, s[48:49]
	v_lshl_add_u64 v[0:1], s[50:51], 2, v[0:1]
	v_lshl_add_u64 v[0:1], v[0:1], 0, v[96:97]
	global_load_dwordx4 v[36:39], v[0:1], off nt
	v_cndmask_b32_e64 v0, 0, 1, s[52:53]
	v_cmp_ne_u32_e64 s[0:1], 1, v0
	s_andn2_b64 vcc, exec, s[52:53]
	v_mov_b32_e32 v118, v116
	s_cbranch_vccnz .LBB0_70
.LBB0_70:
	v_or_b32_e32 v0, 8, v46
	v_mad_u64_u32 v[0:1], s[52:53], v0, s57, 0
	v_mov_b32_e32 v2, v1
	v_mad_u64_u32 v[2:3], s[52:53], v47, s57, v[2:3]
	v_mov_b32_e32 v1, v2
	v_lshl_add_u64 v[0:1], v[0:1], 2, s[48:49]
	v_lshl_add_u64 v[0:1], s[50:51], 2, v[0:1]
	v_lshl_add_u64 v[0:1], v[0:1], 0, v[96:97]
	global_load_dwordx4 v[32:35], v[0:1], off nt
	s_and_b64 vcc, exec, s[0:1]
	v_mov_b32_e32 v120, v116
	s_cbranch_vccnz .LBB0_72
.LBB0_72:
	v_or_b32_e32 v0, 16, v46
	v_mad_u64_u32 v[0:1], s[52:53], v0, s57, 0
	v_mov_b32_e32 v2, v1
	v_mad_u64_u32 v[2:3], s[52:53], v47, s57, v[2:3]
	v_mov_b32_e32 v1, v2
	v_lshl_add_u64 v[0:1], v[0:1], 2, s[48:49]
	v_lshl_add_u64 v[0:1], s[50:51], 2, v[0:1]
	v_lshl_add_u64 v[0:1], v[0:1], 0, v[96:97]
	global_load_dwordx4 v[24:27], v[0:1], off nt
	s_and_b64 vcc, exec, s[0:1]
	v_mov_b32_e32 v122, v116
	s_cbranch_vccnz .LBB0_74
.LBB0_74:
	v_or_b32_e32 v0, 24, v46
	v_mad_u64_u32 v[0:1], s[52:53], v0, s57, 0
	v_mov_b32_e32 v2, v1
	v_mad_u64_u32 v[2:3], s[52:53], v47, s57, v[2:3]
	v_mov_b32_e32 v1, v2
	v_lshl_add_u64 v[0:1], v[0:1], 2, s[48:49]
	v_lshl_add_u64 v[0:1], s[50:51], 2, v[0:1]
	v_lshl_add_u64 v[0:1], v[0:1], 0, v[96:97]
	global_load_dwordx4 v[16:19], v[0:1], off nt
	s_and_b64 vcc, exec, s[0:1]
	v_mov_b32_e32 v126, v116
	s_cbranch_vccnz .LBB0_76
.LBB0_76:
	v_or_b32_e32 v0, 32, v46
	v_mad_u64_u32 v[0:1], s[52:53], v0, s57, 0
	v_mov_b32_e32 v2, v1
	v_mad_u64_u32 v[2:3], s[52:53], v47, s57, v[2:3]
	v_mov_b32_e32 v1, v2
	v_lshl_add_u64 v[0:1], v[0:1], 2, s[48:49]
	v_lshl_add_u64 v[0:1], s[50:51], 2, v[0:1]
	v_lshl_add_u64 v[0:1], v[0:1], 0, v[96:97]
	global_load_dwordx4 v[8:11], v[0:1], off nt
	s_and_b64 vcc, exec, s[0:1]
	v_mov_b32_e32 v128, v116
	s_cbranch_vccnz .LBB0_78
.LBB0_78:
	v_or_b32_e32 v0, 40, v46
	v_mad_u64_u32 v[0:1], s[52:53], v0, s57, 0
	v_mov_b32_e32 v2, v1
	v_mad_u64_u32 v[2:3], s[52:53], v47, s57, v[2:3]
	v_mov_b32_e32 v1, v2
	v_lshl_add_u64 v[0:1], v[0:1], 2, s[48:49]
	v_lshl_add_u64 v[0:1], s[50:51], 2, v[0:1]
	v_lshl_add_u64 v[0:1], v[0:1], 0, v[96:97]
	global_load_dwordx4 v[4:7], v[0:1], off nt
	s_and_b64 vcc, exec, s[0:1]
	v_mov_b32_e32 v130, v116
	s_cbranch_vccnz .LBB0_80
.LBB0_80:
	v_or_b32_e32 v0, 48, v46
	v_mad_u64_u32 v[0:1], s[52:53], v0, s57, 0
	v_mov_b32_e32 v2, v1
	v_mad_u64_u32 v[2:3], s[52:53], v47, s57, v[2:3]
	v_mov_b32_e32 v1, v2
	v_lshl_add_u64 v[0:1], v[0:1], 2, s[48:49]
	v_lshl_add_u64 v[0:1], s[50:51], 2, v[0:1]
	v_lshl_add_u64 v[0:1], v[0:1], 0, v[96:97]
	global_load_dwordx4 v[0:3], v[0:1], off nt
	s_and_b64 vcc, exec, s[0:1]
	s_cbranch_vccnz .LBB0_82
	s_waitcnt vmcnt(7)
	v_mul_f32_e32 v44, v116, v148
	v_mul_f32_e32 v118, v116, v149
	v_mul_f32_e32 v120, v116, v150
	v_mul_f32_e32 v122, v116, v151
	v_mul_f32_e32 v126, v116, v152
	v_mul_f32_e32 v128, v116, v153
	v_mul_f32_e32 v130, v116, v154
	v_mul_f32_e32 v116, v116, v155

.Lgh2_skip:
	s_cbranch_scc1 .LBB0_98
.LBB0_98:
	v_mad_u64_u32 v[12:13], s[0:1], v62, s59, 0
	v_mov_b32_e32 v14, v13
	v_mad_u64_u32 v[14:15], s[0:1], v63, s59, v[14:15]
	s_lshl_b32 s52, s45, 5
	v_mov_b32_e32 v13, v14
	s_ashr_i32 s53, s52, 31
	v_lshl_add_u64 v[12:13], v[12:13], 2, s[50:51]
	v_lshl_add_u64 v[12:13], s[52:53], 2, v[12:13]
	v_lshl_add_u64 v[12:13], v[12:13], 0, v[96:97]
	global_load_dwordx4 v[56:59], v[12:13], off nt
	v_cndmask_b32_e64 v12, 0, 1, s[54:55]
	v_cmp_ne_u32_e64 s[0:1], 1, v12
	s_andn2_b64 vcc, exec, s[54:55]
	v_mov_b32_e32 v118, v116
	s_cbranch_vccnz .LBB0_100
.LBB0_100:
	v_or_b32_e32 v12, 8, v62
	v_mad_u64_u32 v[12:13], s[54:55], v12, s59, 0
	v_mov_b32_e32 v14, v13
	v_mad_u64_u32 v[14:15], s[54:55], v63, s59, v[14:15]
	v_mov_b32_e32 v13, v14
	v_lshl_add_u64 v[12:13], v[12:13], 2, s[50:51]
	v_lshl_add_u64 v[12:13], s[52:53], 2, v[12:13]
	v_lshl_add_u64 v[12:13], v[12:13], 0, v[96:97]
	global_load_dwordx4 v[52:55], v[12:13], off nt
	s_and_b64 vcc, exec, s[0:1]
	v_mov_b32_e32 v120, v116
	s_cbranch_vccnz .LBB0_102
.LBB0_102:
	v_or_b32_e32 v12, 16, v62
	v_mad_u64_u32 v[12:13], s[54:55], v12, s59, 0
	v_mov_b32_e32 v14, v13
	v_mad_u64_u32 v[14:15], s[54:55], v63, s59, v[14:15]
	v_mov_b32_e32 v13, v14
	v_lshl_add_u64 v[12:13], v[12:13], 2, s[50:51]
	v_lshl_add_u64 v[12:13], s[52:53], 2, v[12:13]
	v_lshl_add_u64 v[12:13], v[12:13], 0, v[96:97]
	global_load_dwordx4 v[48:51], v[12:13], off nt
	s_and_b64 vcc, exec, s[0:1]
	v_mov_b32_e32 v122, v116
	s_cbranch_vccnz .LBB0_104
.LBB0_104:
	v_or_b32_e32 v12, 24, v62
	v_mad_u64_u32 v[12:13], s[54:55], v12, s59, 0
	v_mov_b32_e32 v14, v13
	v_mad_u64_u32 v[14:15], s[54:55], v63, s59, v[14:15]
	v_mov_b32_e32 v13, v14
	v_lshl_add_u64 v[12:13], v[12:13], 2, s[50:51]
	v_lshl_add_u64 v[12:13], s[52:53], 2, v[12:13]
	v_lshl_add_u64 v[12:13], v[12:13], 0, v[96:97]
	global_load_dwordx4 v[40:43], v[12:13], off nt
	s_and_b64 vcc, exec, s[0:1]
	v_mov_b32_e32 v126, v116
	s_cbranch_vccnz .LBB0_106
.LBB0_106:
	v_or_b32_e32 v12, 32, v62
	v_mad_u64_u32 v[12:13], s[54:55], v12, s59, 0
	v_mov_b32_e32 v14, v13
	v_mad_u64_u32 v[14:15], s[54:55], v63, s59, v[14:15]
	v_mov_b32_e32 v13, v14
	v_lshl_add_u64 v[12:13], v[12:13], 2, s[50:51]
	v_lshl_add_u64 v[12:13], s[52:53], 2, v[12:13]
	v_lshl_add_u64 v[12:13], v[12:13], 0, v[96:97]
	global_load_dwordx4 v[28:31], v[12:13], off nt
	s_and_b64 vcc, exec, s[0:1]
	v_mov_b32_e32 v128, v116
	s_cbranch_vccnz .LBB0_108
.LBB0_108:
	v_or_b32_e32 v12, 40, v62
	v_mad_u64_u32 v[12:13], s[54:55], v12, s59, 0
	v_mov_b32_e32 v14, v13
	v_mad_u64_u32 v[14:15], s[54:55], v63, s59, v[14:15]
	v_mov_b32_e32 v13, v14
	v_lshl_add_u64 v[12:13], v[12:13], 2, s[50:51]
	v_lshl_add_u64 v[12:13], s[52:53], 2, v[12:13]
	v_lshl_add_u64 v[12:13], v[12:13], 0, v[96:97]
	global_load_dwordx4 v[20:23], v[12:13], off nt
	s_and_b64 vcc, exec, s[0:1]
	v_mov_b32_e32 v130, v116
	s_cbranch_vccnz .LBB0_110
.LBB0_110:
	v_or_b32_e32 v12, 48, v62
	v_mad_u64_u32 v[12:13], s[54:55], v12, s59, 0
	v_mov_b32_e32 v14, v13
	v_mad_u64_u32 v[14:15], s[54:55], v63, s59, v[14:15]
	v_mov_b32_e32 v13, v14
	v_lshl_add_u64 v[12:13], v[12:13], 2, s[50:51]
	v_lshl_add_u64 v[12:13], s[52:53], 2, v[12:13]
	v_lshl_add_u64 v[12:13], v[12:13], 0, v[96:97]
	global_load_dwordx4 v[12:15], v[12:13], off nt
	s_and_b64 vcc, exec, s[0:1]
	s_cbranch_vccnz .LBB0_112
	s_waitcnt vmcnt(7)
	v_mul_f32_e32 v60, v116, v156
	v_mul_f32_e32 v118, v116, v157
	v_mul_f32_e32 v120, v116, v158
	v_mul_f32_e32 v122, v116, v159
	v_mul_f32_e32 v126, v116, v160
	v_mul_f32_e32 v128, v116, v161
	v_mul_f32_e32 v130, v116, v162
	v_mul_f32_e32 v116, v116, v163
